# P1 schedule: two conv-tile units swapped away from the two workgroups that had five
# speedup vs baseline: 1.0001x; 1.0001x over previous
;     __host__ __device__ bool next(int i, Unit& u) const {
;         const long L = (long)i * G + c; if (L >= nwg) return false;
;         int wgid = (int)L; { const int q = nwg / NXCD, r = nwg % NXCD, xcd = wgid % NXCD, off = wgid / NXCD; wgid = (xcd < r ? xcd * (q + 1) : r * (q + 1) + (xcd - r) * q) + off; }
; template <class Epi, class Sched, bool ALIGN_EPI = true>
; __device__ __forceinline__ void gemm_phase(LAS unsigned char* lds, const Gemm g, const Sched& S, const Epi& E) {
;     ...
;         const bool has_next = S.next(ui + 1, nxt);
.LBB0_125:
	s_add_i32 s29, s29, 1
	s_mul_i32 s0, s29, s45
	s_mul_hi_u32 s1, s29, s46
	s_add_i32 s1, s1, s0
	s_mul_i32 s0, s29, s46
	s_add_u32 s0, s0, s88
	s_addc_u32 s1, s1, s47
	s_mov_b32 s98, s0
	s_cmp_eq_u32 s0, 0x497
	s_cselect_b32 s98, 0x2f7, s98
	s_cmp_eq_u32 s0, 0x2f7
	s_cselect_b32 s98, 0x497, s98
	s_cmp_eq_u32 s0, 0x49f
	s_cselect_b32 s98, 0x2ff, s98
	s_cmp_eq_u32 s0, 0x2ff
	s_cselect_b32 s98, 0x49f, s98
	s_mov_b32 s0, s98
	v_cmp_gt_i64_e32 vcc, s[0:1], v[144:145]
	v_cmp_lt_i64_e64 s[4:5], s[0:1], v[142:143]
	s_cbranch_vccnz .LBB0_131
	s_ashr_i32 s1, s0, 31
	s_lshr_b32 s1, s1, 29
	s_add_i32 s3, s0, s1
	s_and_b32 s1, s3, -8
	s_sub_i32 s16, s0, s1
	s_cmp_gt_i32 s16, 4
	s_mov_b64 s[0:1], -1
	s_cbranch_scc0 .LBB0_128
	s_mul_i32 s0, s16, 0x178
	s_or_b32 s17, s0, 5
	s_mov_b64 s[0:1], 0
